# attention phase: static s_setprio 1 for waves 0-3 (first query half) instead; on top of v94
# speedup vs baseline: 1.0157x; 1.0027x over previous
.LBB0_1179:
	s_or_b64 exec, exec, s[2:3]
	s_waitcnt lgkmcnt(0)
	s_barrier
	s_getreg_b32 s0, hwreg(HW_REG_HW_ID, 0, 6)
	s_and_b32 s0, s0, 63
	s_lshl_b32 s0, s0, 2
	s_add_i32 s0, s0, 0
	s_add_i32 s0, s0, 0x22ef0
	v_mov_b32_e32 v0, s0
	ds_read_b32 v0, v0
	v_mov_b32_e32 v1, v177
	v_readlane_b32 s2, v253, 1
	v_readlane_b32 s3, v253, 2
	s_waitcnt lgkmcnt(0)
	v_readfirstlane_b32 s0, v0
	v_mbcnt_lo_u32_b32 v0, -1, v1
	v_mbcnt_hi_u32_b32 v0, -1, v0
	v_lshl_add_u32 v0, s0, 6, v0
	s_cmp_ge_u32 s0, 4
	s_cbranch_scc1 .Lattn_prio_done
	s_setprio 1
